# prologue de-serialisation in the LRU per-direction setup: 16 gate-weight loads and 12 bias/softplus loads issued up front with counted waits (was one exposed load latency per step)
# speedup vs baseline: 1.0044x; 1.0044x over previous
; __device__ __forceinline__ u16 f2bf(float f) { unsigned u = __float_as_uint(f); u += 0x7FFFu + ((u >> 16) & 1u); return (u16)(u >> 16); }
; __device__ __forceinline__ void lru_phase(const Args& A, unsigned char* smem, const bool dry) {
;     ...
;             for (int e = tid; e < 8192; e += 512) { const int gate = e >> 12, c = (e >> 6) & 63, d = e & 63;
;                 const float v = (gate ? A.in[10] : A.in[8])[(size_t)((dir * 16 + nb) * 64 + c) * 64 + d]; wT[(gate * 64 + d) * 72 + c] = f2bf(v); }
.LBB0_489:
	v_lshrrev_b32_e32 v3, 6, v1
	s_waitcnt lgkmcnt(0)
	v_lshrrev_b32_e32 v10, 6, v0
	s_waitcnt vmcnt(0)
	v_mov_b32_e32 v4, s26
	v_mov_b32_e32 v8, s22
	v_cmp_gt_u32_e32 vcc, s29, v0
	v_mov_b32_e32 v6, s28
	v_mov_b32_e32 v7, s24
	v_cmp_gt_u32_e64 s[8:9], s29, v1
	v_mov_b32_e32 v9, s27
	v_mov_b32_e32 v11, s23
	v_and_b32_e32 v14, 63, v3
	v_and_b32_e32 v15, 63, v10
	v_cndmask_b32_e64 v7, v6, v7, s[8:9]
	v_cndmask_b32_e64 v6, v9, v11, s[8:9]
	v_cndmask_b32_e32 v9, v4, v8, vcc
	v_or_b32_e32 v4, s20, v14
	v_or_b32_e32 v11, s12, v15
	v_lshlrev_b32_e32 v4, 6, v4
	v_mov_b32_e32 v12, s25
	v_mov_b32_e32 v13, s15
	v_mov_b32_e32 v5, v43
	v_lshlrev_b32_e32 v11, 6, v11
	v_or_b32_e32 v4, v4, v41
	v_cndmask_b32_e32 v8, v12, v13, vcc
	v_or_b32_e32 v42, v11, v40
	v_lshl_add_u64 v[4:5], v[4:5], 2, v[6:7]
	v_lshl_add_u64 v[8:9], v[42:43], 2, v[8:9]
	global_load_dword v176, v[4:5], off
	s_nop 0
	global_load_dword v177, v[8:9], off
	v_and_b32_e32 v3, 64, v3
	v_and_b32_e32 v6, 64, v10
	v_or_b32_e32 v3, v3, v41
	v_add_u32_e32 v2, -2, v2
	v_or_b32_e32 v6, v6, v40
	v_lshlrev_b32_e32 v8, 1, v14
	v_mul_u32_u24_e32 v3, 0x90, v3
	v_lshlrev_b32_e32 v7, 1, v15
	v_mul_u32_u24_e32 v6, 0x90, v6
	v_add3_u32 v3, 0, v3, v8
	v_add_u32_e32 v1, 0x400, v1
	v_add_u32_e32 v0, 0x400, v0
	v_add3_u32 v6, 0, v6, v7
	v_mov_b32_e32 v192, v3
	v_mov_b32_e32 v193, v6
	v_lshrrev_b32_e32 v3, 6, v1
	v_lshrrev_b32_e32 v10, 6, v0
	v_mov_b32_e32 v4, s26
	v_mov_b32_e32 v8, s22
	v_cmp_gt_u32_e32 vcc, s29, v0
	v_mov_b32_e32 v6, s28
	v_mov_b32_e32 v7, s24
	v_cmp_gt_u32_e64 s[8:9], s29, v1
	v_mov_b32_e32 v9, s27
	v_mov_b32_e32 v11, s23
	v_and_b32_e32 v14, 63, v3
	v_and_b32_e32 v15, 63, v10
	v_cndmask_b32_e64 v7, v6, v7, s[8:9]
	v_cndmask_b32_e64 v6, v9, v11, s[8:9]
	v_cndmask_b32_e32 v9, v4, v8, vcc
	v_or_b32_e32 v4, s20, v14
	v_or_b32_e32 v11, s12, v15
	v_lshlrev_b32_e32 v4, 6, v4
	v_mov_b32_e32 v12, s25
	v_mov_b32_e32 v13, s15
	v_mov_b32_e32 v5, v43
	v_lshlrev_b32_e32 v11, 6, v11
	v_or_b32_e32 v4, v4, v41
	v_cndmask_b32_e32 v8, v12, v13, vcc
	v_or_b32_e32 v42, v11, v40
	v_lshl_add_u64 v[4:5], v[4:5], 2, v[6:7]
	v_lshl_add_u64 v[8:9], v[42:43], 2, v[8:9]
	global_load_dword v178, v[4:5], off
	s_nop 0
	global_load_dword v179, v[8:9], off
	v_and_b32_e32 v3, 64, v3
	v_and_b32_e32 v6, 64, v10
	v_or_b32_e32 v3, v3, v41
	v_add_u32_e32 v2, -2, v2
	v_or_b32_e32 v6, v6, v40
	v_lshlrev_b32_e32 v8, 1, v14
	v_mul_u32_u24_e32 v3, 0x90, v3
	v_lshlrev_b32_e32 v7, 1, v15
	v_mul_u32_u24_e32 v6, 0x90, v6
	v_add3_u32 v3, 0, v3, v8
	v_add_u32_e32 v1, 0x400, v1
	v_add_u32_e32 v0, 0x400, v0
	v_add3_u32 v6, 0, v6, v7
	v_mov_b32_e32 v194, v3
	v_mov_b32_e32 v195, v6
	v_lshrrev_b32_e32 v3, 6, v1
	v_lshrrev_b32_e32 v10, 6, v0
	v_mov_b32_e32 v4, s26
	v_mov_b32_e32 v8, s22
	v_cmp_gt_u32_e32 vcc, s29, v0
	v_mov_b32_e32 v6, s28
	v_mov_b32_e32 v7, s24
	v_cmp_gt_u32_e64 s[8:9], s29, v1
	v_mov_b32_e32 v9, s27
	v_mov_b32_e32 v11, s23
	v_and_b32_e32 v14, 63, v3
	v_and_b32_e32 v15, 63, v10
	v_cndmask_b32_e64 v7, v6, v7, s[8:9]
	v_cndmask_b32_e64 v6, v9, v11, s[8:9]
	v_cndmask_b32_e32 v9, v4, v8, vcc
	v_or_b32_e32 v4, s20, v14
	v_or_b32_e32 v11, s12, v15
	v_lshlrev_b32_e32 v4, 6, v4
	v_mov_b32_e32 v12, s25
	v_mov_b32_e32 v13, s15
	v_mov_b32_e32 v5, v43
	v_lshlrev_b32_e32 v11, 6, v11
	v_or_b32_e32 v4, v4, v41
	v_cndmask_b32_e32 v8, v12, v13, vcc
	v_or_b32_e32 v42, v11, v40
	v_lshl_add_u64 v[4:5], v[4:5], 2, v[6:7]
	v_lshl_add_u64 v[8:9], v[42:43], 2, v[8:9]
	global_load_dword v180, v[4:5], off
	s_nop 0
	global_load_dword v181, v[8:9], off
	v_and_b32_e32 v3, 64, v3
	v_and_b32_e32 v6, 64, v10
	v_or_b32_e32 v3, v3, v41
	v_add_u32_e32 v2, -2, v2
	v_or_b32_e32 v6, v6, v40
	v_lshlrev_b32_e32 v8, 1, v14
	v_mul_u32_u24_e32 v3, 0x90, v3
	v_lshlrev_b32_e32 v7, 1, v15
	v_mul_u32_u24_e32 v6, 0x90, v6
	v_add3_u32 v3, 0, v3, v8
	v_add_u32_e32 v1, 0x400, v1
	v_add_u32_e32 v0, 0x400, v0
	v_add3_u32 v6, 0, v6, v7
	v_mov_b32_e32 v196, v3
	v_mov_b32_e32 v197, v6
	v_lshrrev_b32_e32 v3, 6, v1
	v_lshrrev_b32_e32 v10, 6, v0
	v_mov_b32_e32 v4, s26
	v_mov_b32_e32 v8, s22
	v_cmp_gt_u32_e32 vcc, s29, v0
	v_mov_b32_e32 v6, s28
	v_mov_b32_e32 v7, s24
	v_cmp_gt_u32_e64 s[8:9], s29, v1
	v_mov_b32_e32 v9, s27
	v_mov_b32_e32 v11, s23
	v_and_b32_e32 v14, 63, v3
	v_and_b32_e32 v15, 63, v10
	v_cndmask_b32_e64 v7, v6, v7, s[8:9]
	v_cndmask_b32_e64 v6, v9, v11, s[8:9]
	v_cndmask_b32_e32 v9, v4, v8, vcc
	v_or_b32_e32 v4, s20, v14
	v_or_b32_e32 v11, s12, v15
	v_lshlrev_b32_e32 v4, 6, v4
	v_mov_b32_e32 v12, s25
	v_mov_b32_e32 v13, s15
	v_mov_b32_e32 v5, v43
	v_lshlrev_b32_e32 v11, 6, v11
	v_or_b32_e32 v4, v4, v41
	v_cndmask_b32_e32 v8, v12, v13, vcc
	v_or_b32_e32 v42, v11, v40
	v_lshl_add_u64 v[4:5], v[4:5], 2, v[6:7]
	v_lshl_add_u64 v[8:9], v[42:43], 2, v[8:9]
	global_load_dword v182, v[4:5], off
	s_nop 0
	global_load_dword v183, v[8:9], off
	v_and_b32_e32 v3, 64, v3
	v_and_b32_e32 v6, 64, v10
	v_or_b32_e32 v3, v3, v41
	v_add_u32_e32 v2, -2, v2
	v_or_b32_e32 v6, v6, v40
	v_lshlrev_b32_e32 v8, 1, v14
	v_mul_u32_u24_e32 v3, 0x90, v3
	v_lshlrev_b32_e32 v7, 1, v15
	v_mul_u32_u24_e32 v6, 0x90, v6
	v_add3_u32 v3, 0, v3, v8
	v_add_u32_e32 v1, 0x400, v1
	v_add_u32_e32 v0, 0x400, v0
	v_add3_u32 v6, 0, v6, v7
	v_mov_b32_e32 v198, v3
	v_mov_b32_e32 v199, v6
	v_lshrrev_b32_e32 v3, 6, v1
	v_lshrrev_b32_e32 v10, 6, v0
	v_mov_b32_e32 v4, s26
	v_mov_b32_e32 v8, s22
	v_cmp_gt_u32_e32 vcc, s29, v0
	v_mov_b32_e32 v6, s28
	v_mov_b32_e32 v7, s24
	v_cmp_gt_u32_e64 s[8:9], s29, v1
	v_mov_b32_e32 v9, s27
	v_mov_b32_e32 v11, s23
	v_and_b32_e32 v14, 63, v3
	v_and_b32_e32 v15, 63, v10
	v_cndmask_b32_e64 v7, v6, v7, s[8:9]
	v_cndmask_b32_e64 v6, v9, v11, s[8:9]
	v_cndmask_b32_e32 v9, v4, v8, vcc
; __device__ __forceinline__ u16 f2bf(float f) { unsigned u = __float_as_uint(f); u += 0x7FFFu + ((u >> 16) & 1u); return (u16)(u >> 16); }
; __device__ __forceinline__ void lru_phase(const Args& A, unsigned char* smem, const bool dry) {
;     ...
;             for (int e = tid; e < 8192; e += 512) { const int gate = e >> 12, c = (e >> 6) & 63, d = e & 63;
;                 const float v = (gate ? A.in[10] : A.in[8])[(size_t)((dir * 16 + nb) * 64 + c) * 64 + d]; wT[(gate * 64 + d) * 72 + c] = f2bf(v); }
	v_or_b32_e32 v4, s20, v14
	v_or_b32_e32 v11, s12, v15
	v_lshlrev_b32_e32 v4, 6, v4
	v_mov_b32_e32 v12, s25
	v_mov_b32_e32 v13, s15
	v_mov_b32_e32 v5, v43
	v_lshlrev_b32_e32 v11, 6, v11
	v_or_b32_e32 v4, v4, v41
	v_cndmask_b32_e32 v8, v12, v13, vcc
	v_or_b32_e32 v42, v11, v40
	v_lshl_add_u64 v[4:5], v[4:5], 2, v[6:7]
	v_lshl_add_u64 v[8:9], v[42:43], 2, v[8:9]
	global_load_dword v184, v[4:5], off
	s_nop 0
	global_load_dword v185, v[8:9], off
	v_and_b32_e32 v3, 64, v3
	v_and_b32_e32 v6, 64, v10
	v_or_b32_e32 v3, v3, v41
	v_add_u32_e32 v2, -2, v2
	v_or_b32_e32 v6, v6, v40
	v_lshlrev_b32_e32 v8, 1, v14
	v_mul_u32_u24_e32 v3, 0x90, v3
	v_lshlrev_b32_e32 v7, 1, v15
	v_mul_u32_u24_e32 v6, 0x90, v6
	v_add3_u32 v3, 0, v3, v8
	v_add_u32_e32 v1, 0x400, v1
	v_add_u32_e32 v0, 0x400, v0
	v_add3_u32 v6, 0, v6, v7
	v_mov_b32_e32 v200, v3
	v_mov_b32_e32 v201, v6
	v_lshrrev_b32_e32 v3, 6, v1
	v_lshrrev_b32_e32 v10, 6, v0
	v_mov_b32_e32 v4, s26
	v_mov_b32_e32 v8, s22
	v_cmp_gt_u32_e32 vcc, s29, v0
	v_mov_b32_e32 v6, s28
	v_mov_b32_e32 v7, s24
	v_cmp_gt_u32_e64 s[8:9], s29, v1
	v_mov_b32_e32 v9, s27
	v_mov_b32_e32 v11, s23
	v_and_b32_e32 v14, 63, v3
	v_and_b32_e32 v15, 63, v10
	v_cndmask_b32_e64 v7, v6, v7, s[8:9]
	v_cndmask_b32_e64 v6, v9, v11, s[8:9]
	v_cndmask_b32_e32 v9, v4, v8, vcc
	v_or_b32_e32 v4, s20, v14
	v_or_b32_e32 v11, s12, v15
	v_lshlrev_b32_e32 v4, 6, v4
	v_mov_b32_e32 v12, s25
	v_mov_b32_e32 v13, s15
	v_mov_b32_e32 v5, v43
	v_lshlrev_b32_e32 v11, 6, v11
	v_or_b32_e32 v4, v4, v41
	v_cndmask_b32_e32 v8, v12, v13, vcc
	v_or_b32_e32 v42, v11, v40
	v_lshl_add_u64 v[4:5], v[4:5], 2, v[6:7]
	v_lshl_add_u64 v[8:9], v[42:43], 2, v[8:9]
	global_load_dword v186, v[4:5], off
	s_nop 0
	global_load_dword v187, v[8:9], off
	v_and_b32_e32 v3, 64, v3
	v_and_b32_e32 v6, 64, v10
	v_or_b32_e32 v3, v3, v41
	v_add_u32_e32 v2, -2, v2
	v_or_b32_e32 v6, v6, v40
	v_lshlrev_b32_e32 v8, 1, v14
	v_mul_u32_u24_e32 v3, 0x90, v3
	v_lshlrev_b32_e32 v7, 1, v15
	v_mul_u32_u24_e32 v6, 0x90, v6
	v_add3_u32 v3, 0, v3, v8
	v_add_u32_e32 v1, 0x400, v1
	v_add_u32_e32 v0, 0x400, v0
	v_add3_u32 v6, 0, v6, v7
	v_mov_b32_e32 v202, v3
	v_mov_b32_e32 v203, v6
	v_lshrrev_b32_e32 v3, 6, v1
	v_lshrrev_b32_e32 v10, 6, v0
	v_mov_b32_e32 v4, s26
	v_mov_b32_e32 v8, s22
	v_cmp_gt_u32_e32 vcc, s29, v0
	v_mov_b32_e32 v6, s28
	v_mov_b32_e32 v7, s24
	v_cmp_gt_u32_e64 s[8:9], s29, v1
	v_mov_b32_e32 v9, s27
	v_mov_b32_e32 v11, s23
	v_and_b32_e32 v14, 63, v3
	v_and_b32_e32 v15, 63, v10
	v_cndmask_b32_e64 v7, v6, v7, s[8:9]
	v_cndmask_b32_e64 v6, v9, v11, s[8:9]
	v_cndmask_b32_e32 v9, v4, v8, vcc
	v_or_b32_e32 v4, s20, v14
	v_or_b32_e32 v11, s12, v15
	v_lshlrev_b32_e32 v4, 6, v4
	v_mov_b32_e32 v12, s25
	v_mov_b32_e32 v13, s15
	v_mov_b32_e32 v5, v43
	v_lshlrev_b32_e32 v11, 6, v11
	v_or_b32_e32 v4, v4, v41
	v_cndmask_b32_e32 v8, v12, v13, vcc
	v_or_b32_e32 v42, v11, v40
	v_lshl_add_u64 v[4:5], v[4:5], 2, v[6:7]
	v_lshl_add_u64 v[8:9], v[42:43], 2, v[8:9]
	global_load_dword v188, v[4:5], off
	s_nop 0
	global_load_dword v189, v[8:9], off
	v_and_b32_e32 v3, 64, v3
	v_and_b32_e32 v6, 64, v10
	v_or_b32_e32 v3, v3, v41
	v_add_u32_e32 v2, -2, v2
	v_or_b32_e32 v6, v6, v40
	v_lshlrev_b32_e32 v8, 1, v14
	v_mul_u32_u24_e32 v3, 0x90, v3
	v_lshlrev_b32_e32 v7, 1, v15
	v_mul_u32_u24_e32 v6, 0x90, v6
	v_add3_u32 v3, 0, v3, v8
	v_add_u32_e32 v1, 0x400, v1
	v_add_u32_e32 v0, 0x400, v0
	v_add3_u32 v6, 0, v6, v7
	v_mov_b32_e32 v204, v3
	v_mov_b32_e32 v205, v6
	v_lshrrev_b32_e32 v3, 6, v1
	v_lshrrev_b32_e32 v10, 6, v0
	v_mov_b32_e32 v4, s26
	v_mov_b32_e32 v8, s22
	v_cmp_gt_u32_e32 vcc, s29, v0
	v_mov_b32_e32 v6, s28
	v_mov_b32_e32 v7, s24
	v_cmp_gt_u32_e64 s[8:9], s29, v1
	v_mov_b32_e32 v9, s27
	v_mov_b32_e32 v11, s23
	v_and_b32_e32 v14, 63, v3
	v_and_b32_e32 v15, 63, v10
	v_cndmask_b32_e64 v7, v6, v7, s[8:9]
	v_cndmask_b32_e64 v6, v9, v11, s[8:9]
	v_cndmask_b32_e32 v9, v4, v8, vcc
	v_or_b32_e32 v4, s20, v14
	v_or_b32_e32 v11, s12, v15
	v_lshlrev_b32_e32 v4, 6, v4
	v_mov_b32_e32 v12, s25
	v_mov_b32_e32 v13, s15
	v_mov_b32_e32 v5, v43
	v_lshlrev_b32_e32 v11, 6, v11
	v_or_b32_e32 v4, v4, v41
	v_cndmask_b32_e32 v8, v12, v13, vcc
	v_or_b32_e32 v42, v11, v40
	v_lshl_add_u64 v[4:5], v[4:5], 2, v[6:7]
	v_lshl_add_u64 v[8:9], v[42:43], 2, v[8:9]
	global_load_dword v190, v[4:5], off
	s_nop 0
	global_load_dword v191, v[8:9], off
	v_and_b32_e32 v3, 64, v3
	v_and_b32_e32 v6, 64, v10
	v_or_b32_e32 v3, v3, v41
	v_add_u32_e32 v2, -2, v2
	v_or_b32_e32 v6, v6, v40
	v_lshlrev_b32_e32 v8, 1, v14
	v_mul_u32_u24_e32 v3, 0x90, v3
	v_lshlrev_b32_e32 v7, 1, v15
	v_mul_u32_u24_e32 v6, 0x90, v6
	v_add3_u32 v3, 0, v3, v8
	v_add_u32_e32 v1, 0x400, v1
	v_add_u32_e32 v0, 0x400, v0
	v_add3_u32 v6, 0, v6, v7
	v_mov_b32_e32 v206, v3
	v_mov_b32_e32 v207, v6
	s_waitcnt vmcnt(0)
; __device__ __forceinline__ u16 f2bf(float f) { unsigned u = __float_as_uint(f); u += 0x7FFFu + ((u >> 16) & 1u); return (u16)(u >> 16); }
; __device__ __forceinline__ void lru_phase(const Args& A, unsigned char* smem, const bool dry) {
;     ...
;             for (int e = tid; e < 8192; e += 512) { const int gate = e >> 12, c = (e >> 6) & 63, d = e & 63;
;                 const float v = (gate ? A.in[10] : A.in[8])[(size_t)((dir * 16 + nb) * 64 + c) * 64 + d]; wT[(gate * 64 + d) * 72 + c] = f2bf(v); }
;             if (tid < 64) hcar[tid] = 0.f;
	v_and_b32_sdwa v7, v176, v139 dst_sel:DWORD dst_unused:UNUSED_PAD src0_sel:WORD_1 src1_sel:DWORD
	v_and_b32_sdwa v8, v177, v139 dst_sel:DWORD dst_unused:UNUSED_PAD src0_sel:WORD_1 src1_sel:DWORD
	v_add3_u32 v177, v177, v8, s30
	v_add3_u32 v176, v176, v7, s30
	ds_write_b16_d16_hi v193, v177
	ds_write_b16_d16_hi v192, v176
	v_and_b32_sdwa v7, v178, v139 dst_sel:DWORD dst_unused:UNUSED_PAD src0_sel:WORD_1 src1_sel:DWORD
	v_and_b32_sdwa v8, v179, v139 dst_sel:DWORD dst_unused:UNUSED_PAD src0_sel:WORD_1 src1_sel:DWORD
	v_add3_u32 v179, v179, v8, s30
	v_add3_u32 v178, v178, v7, s30
	ds_write_b16_d16_hi v195, v179
	ds_write_b16_d16_hi v194, v178
	v_and_b32_sdwa v7, v180, v139 dst_sel:DWORD dst_unused:UNUSED_PAD src0_sel:WORD_1 src1_sel:DWORD
	v_and_b32_sdwa v8, v181, v139 dst_sel:DWORD dst_unused:UNUSED_PAD src0_sel:WORD_1 src1_sel:DWORD
	v_add3_u32 v181, v181, v8, s30
	v_add3_u32 v180, v180, v7, s30
	ds_write_b16_d16_hi v197, v181
	ds_write_b16_d16_hi v196, v180
	v_and_b32_sdwa v7, v182, v139 dst_sel:DWORD dst_unused:UNUSED_PAD src0_sel:WORD_1 src1_sel:DWORD
	v_and_b32_sdwa v8, v183, v139 dst_sel:DWORD dst_unused:UNUSED_PAD src0_sel:WORD_1 src1_sel:DWORD
	v_add3_u32 v183, v183, v8, s30
	v_add3_u32 v182, v182, v7, s30
	ds_write_b16_d16_hi v199, v183
	ds_write_b16_d16_hi v198, v182
	v_and_b32_sdwa v7, v184, v139 dst_sel:DWORD dst_unused:UNUSED_PAD src0_sel:WORD_1 src1_sel:DWORD
	v_and_b32_sdwa v8, v185, v139 dst_sel:DWORD dst_unused:UNUSED_PAD src0_sel:WORD_1 src1_sel:DWORD
	v_add3_u32 v185, v185, v8, s30
	v_add3_u32 v184, v184, v7, s30
	ds_write_b16_d16_hi v201, v185
	ds_write_b16_d16_hi v200, v184
	v_and_b32_sdwa v7, v186, v139 dst_sel:DWORD dst_unused:UNUSED_PAD src0_sel:WORD_1 src1_sel:DWORD
	v_and_b32_sdwa v8, v187, v139 dst_sel:DWORD dst_unused:UNUSED_PAD src0_sel:WORD_1 src1_sel:DWORD
	v_add3_u32 v187, v187, v8, s30
	v_add3_u32 v186, v186, v7, s30
	ds_write_b16_d16_hi v203, v187
	ds_write_b16_d16_hi v202, v186
	v_and_b32_sdwa v7, v188, v139 dst_sel:DWORD dst_unused:UNUSED_PAD src0_sel:WORD_1 src1_sel:DWORD
	v_and_b32_sdwa v8, v189, v139 dst_sel:DWORD dst_unused:UNUSED_PAD src0_sel:WORD_1 src1_sel:DWORD
	v_add3_u32 v189, v189, v8, s30
	v_add3_u32 v188, v188, v7, s30
	ds_write_b16_d16_hi v205, v189
	ds_write_b16_d16_hi v204, v188
	v_and_b32_sdwa v7, v190, v139 dst_sel:DWORD dst_unused:UNUSED_PAD src0_sel:WORD_1 src1_sel:DWORD
	v_and_b32_sdwa v8, v191, v139 dst_sel:DWORD dst_unused:UNUSED_PAD src0_sel:WORD_1 src1_sel:DWORD
	v_add3_u32 v191, v191, v8, s30
	v_add3_u32 v190, v190, v7, s30
	ds_write_b16_d16_hi v207, v191
	ds_write_b16_d16_hi v206, v190
	v_cmp_eq_u32_e32 vcc, 0, v2
	s_mov_b64 s[10:11], exec
	s_or_b64 exec, exec, s[10:11]
	s_and_saveexec_b64 s[8:9], s[6:7]
	v_readlane_b32 s48, v251, 20
	v_readlane_b32 s49, v251, 21
	v_readlane_b32 s52, v251, 24
	v_readlane_b32 s53, v251, 25
	v_readlane_b32 s50, v251, 22
	v_readlane_b32 s51, v251, 23
	v_readlane_b32 s54, v251, 26
	v_readlane_b32 s55, v251, 27
	v_readlane_b32 s56, v251, 28
	v_readlane_b32 s57, v251, 29
	v_readlane_b32 s58, v251, 30
	v_readlane_b32 s59, v251, 31
	v_readlane_b32 s60, v251, 32
	v_readlane_b32 s61, v251, 33
	v_readlane_b32 s62, v251, 34
	v_readlane_b32 s63, v251, 35
	s_cbranch_execz .LBB0_493
	s_mov_b64 s[10:11], 0
	v_mov_b32_e32 v0, v130
	v_mov_b32_e32 v1, v129

; __device__ __forceinline__ void lru_phase(const Args& A, unsigned char* smem, const bool dry) {
;     ...
;             if (tid < 64) hcar[tid] = 0.f;
;             float ba[4], bx[4], sp[4];
; #pragma unroll
;             for (int dt = 0; dt < 4; ++dt) { const int ch = dir * 1024 + 64 * nb + 16 * dt + r16; ba[dt] = A.in[9][ch]; bx[dt] = A.in[11][ch];
;                 const float ml = -A.in[12][ch]; sp[dt] = ml > 20.f ? ml : log1pf(__expf(ml)); }
.LBB0_493:
	s_or_b64 exec, exec, s[8:9]
	s_and_saveexec_b64 s[8:9], s[0:1]
	ds_write_b32 v70, v43
	s_or_b64 exec, exec, s[8:9]
	v_or_b32_e32 v42, s12, v80
	v_readlane_b32 s48, v251, 20
	v_lshlrev_b64 v[4:5], 2, v[42:43]
	v_readlane_b32 s56, v251, 28
	v_readlane_b32 s57, v251, 29
	v_readlane_b32 s50, v251, 22
	v_readlane_b32 s51, v251, 23
	v_readlane_b32 s54, v251, 26
	v_readlane_b32 s55, v251, 27
	v_lshl_add_u64 v[2:3], s[56:57], 0, v[4:5]
	v_lshl_add_u64 v[0:1], s[50:51], 0, v[4:5]
	global_load_dword v6, v[2:3], off
	v_lshl_add_u64 v[4:5], s[54:55], 0, v[4:5]
	global_load_dword v42, v[0:1], off
	global_load_dword v145, v[4:5], off
	global_load_dword v208, v[2:3], off offset:64
	global_load_dword v146, v[0:1], off offset:64
	global_load_dword v147, v[4:5], off offset:64
	global_load_dword v209, v[2:3], off offset:128
	global_load_dword v148, v[0:1], off offset:128
	global_load_dword v149, v[4:5], off offset:128
	global_load_dword v210, v[2:3], off offset:192
	global_load_dword v150, v[0:1], off offset:192
	global_load_dword v151, v[4:5], off offset:192
	v_readlane_b32 s49, v251, 21
	v_readlane_b32 s52, v251, 24
	v_readlane_b32 s53, v251, 25
	v_readlane_b32 s58, v251, 30
	v_readlane_b32 s59, v251, 31
	v_readlane_b32 s60, v251, 32
	v_readlane_b32 s61, v251, 33
	v_readlane_b32 s62, v251, 34
	v_readlane_b32 s63, v251, 35
	s_waitcnt vmcnt(11)
	v_xor_b32_e32 v52, 0x80000000, v6
	v_cmp_ngt_f32_e32 vcc, s34, v6
	s_and_saveexec_b64 s[8:9], vcc
	s_cbranch_execz .LBB0_497
	v_mul_f32_e32 v6, 0xbfb8aa3b, v6
	v_exp_f32_e32 v20, v6
	s_nop 0
	v_add_f32_e32 v8, 1.0, v20
	v_frexp_mant_f32_e32 v10, v8
	v_cvt_f64_f32_e32 v[6:7], v8
	v_frexp_exp_i32_f64_e32 v6, v[6:7]
	v_cmp_gt_f32_e32 vcc, s35, v10
	v_add_f32_e32 v9, -1.0, v8
	v_sub_f32_e32 v11, v9, v8
	v_subbrev_co_u32_e32 v14, vcc, 0, v6, vcc
	v_sub_u32_e32 v6, 0, v14
	v_sub_f32_e32 v9, v20, v9
	v_add_f32_e32 v11, 1.0, v11
	v_ldexp_f32 v7, v8, v6
	v_add_f32_e32 v9, v9, v11
	v_add_f32_e32 v8, -1.0, v7
	v_add_f32_e32 v10, 1.0, v7
	v_ldexp_f32 v6, v9, v6
	v_add_f32_e32 v9, 1.0, v8
	v_add_f32_e32 v11, -1.0, v10
	v_sub_f32_e32 v9, v7, v9
	v_sub_f32_e32 v7, v7, v11
	v_add_f32_e32 v9, v6, v9
	v_add_f32_e32 v6, v6, v7
	v_add_f32_e32 v15, v10, v6
	v_rcp_f32_e32 v17, v15
	v_sub_f32_e32 v7, v15, v10
	v_sub_f32_e32 v16, v6, v7
	v_add_f32_e32 v7, v8, v9
	v_mul_f32_e32 v19, v7, v17
	v_sub_f32_e32 v6, v7, v8
	v_mul_f32_e32 v8, v15, v19
	v_fma_f32 v10, v19, v15, -v8
	v_fmac_f32_e32 v10, v19, v16
	v_sub_f32_e32 v18, v9, v6
	v_add_f32_e32 v6, v8, v10
	v_sub_f32_e32 v9, v7, v6
	v_pk_add_f32 v[12:13], v[6:7], v[8:9] neg_lo:[0,1] neg_hi:[0,1]
	v_mov_b32_e32 v11, v6
	v_pk_add_f32 v[6:7], v[12:13], v[10:11] neg_lo:[0,1] neg_hi:[0,1]
	v_cmp_neq_f32_e32 vcc, s37, v20
	v_add_f32_e32 v7, v18, v7
	v_add_f32_e32 v6, v6, v7
	v_add_f32_e32 v7, v9, v6
	v_mul_f32_e32 v18, v17, v7
	v_mul_f32_e32 v8, v15, v18
	v_fma_f32 v10, v18, v15, -v8
	v_fmac_f32_e32 v10, v18, v16
	v_sub_f32_e32 v9, v9, v7
	v_add_f32_e32 v15, v6, v9
	v_add_f32_e32 v6, v8, v10
	v_sub_f32_e32 v9, v7, v6
	v_pk_add_f32 v[12:13], v[6:7], v[8:9] neg_lo:[0,1] neg_hi:[0,1]
	v_mov_b32_e32 v11, v6
	v_pk_add_f32 v[6:7], v[12:13], v[10:11] neg_lo:[0,1] neg_hi:[0,1]
	s_nop 0
	v_add_f32_e32 v7, v15, v7
	v_add_f32_e32 v6, v6, v7
	v_add_f32_e32 v7, v19, v18
	v_add_f32_e32 v6, v9, v6
	v_sub_f32_e32 v8, v7, v19
	v_mul_f32_e32 v6, v17, v6
	v_sub_f32_e32 v8, v18, v8
	v_add_f32_e32 v8, v8, v6
	v_add_f32_e32 v10, v7, v8
	v_mul_f32_e32 v11, v10, v10
	v_fmamk_f32 v6, v11, 0x3e9b6dac, v132
	v_fmaak_f32 v49, v11, v6, 0x3f2aaada
	v_cvt_f32_i32_e32 v6, v14
	v_sub_f32_e32 v7, v10, v7
	v_sub_f32_e32 v7, v8, v7
	v_ldexp_f32 v12, v7, 1
	v_mul_f32_e32 v7, v10, v11
	v_ldexp_f32 v9, v10, 1
	v_pk_mul_f32 v[10:11], v[6:7], v[48:49]
	s_nop 0
	v_fma_f32 v8, v6, s36, -v10
	v_fmac_f32_e32 v8, 0xb102e308, v6
	v_pk_add_f32 v[6:7], v[10:11], v[8:9]
	s_nop 0
	v_sub_f32_e32 v9, v7, v9
	v_sub_f32_e32 v9, v11, v9
	v_add_f32_e32 v13, v12, v9
	v_mov_b32_e32 v12, v10
	v_pk_add_f32 v[10:11], v[6:7], v[10:11] neg_lo:[0,1] neg_hi:[0,1]
	v_pk_add_f32 v[14:15], v[6:7], v[12:13]
	v_mov_b32_e32 v9, v6
	v_mov_b32_e32 v11, v15
	v_pk_add_f32 v[16:17], v[8:9], v[10:11] neg_lo:[0,1] neg_hi:[0,1]
	v_pk_add_f32 v[8:9], v[8:9], v[10:11]
	v_mov_b32_e32 v12, v13
	v_pk_add_f32 v[10:11], v[8:9], v[6:7] op_sel:[1,0] op_sel_hi:[0,1] neg_lo:[0,1] neg_hi:[0,1]
	v_pk_add_f32 v[18:19], v[14:15], v[10:11] op_sel_hi:[1,0] neg_lo:[0,1] neg_hi:[0,1]
	v_mov_b32_e32 v14, v15
	v_mov_b32_e32 v15, v9
	v_pk_mov_b32 v[10:11], v[6:7], v[10:11] op_sel:[1,0]
	v_mov_b32_e32 v13, v6
	v_pk_add_f32 v[10:11], v[14:15], v[10:11] neg_lo:[0,1] neg_hi:[0,1]
	v_mov_b32_e32 v18, v16
	v_pk_add_f32 v[6:7], v[12:13], v[10:11] neg_lo:[0,1] neg_hi:[0,1]
	v_mov_b32_e32 v17, v9
	v_pk_add_f32 v[10:11], v[18:19], v[6:7]
	s_nop 0
	v_pk_add_f32 v[12:13], v[10:11], v[10:11] op_sel:[0,1] op_sel_hi:[1,0]
	s_nop 0
	v_pk_add_f32 v[8:9], v[8:9], v[12:13] op_sel:[1,0] op_sel_hi:[0,1]
	v_mov_b32_e32 v11, v8
	v_pk_add_f32 v[14:15], v[10:11], v[16:17] neg_lo:[0,1] neg_hi:[0,1]
	v_mov_b32_e32 v7, v12
	v_sub_f32_e32 v9, v10, v14
	v_pk_add_f32 v[6:7], v[6:7], v[14:15] neg_lo:[0,1] neg_hi:[0,1]
	v_sub_f32_e32 v9, v16, v9
	v_add_f32_e32 v6, v6, v9
	v_add_f32_e32 v6, v6, v7
	v_add_f32_e32 v6, v8, v6
	v_cndmask_b32_e32 v6, v140, v6, vcc
	v_cmp_ngt_f32_e32 vcc, -1.0, v20
	s_nop 1
	v_cndmask_b32_e32 v6, v141, v6, vcc
	v_cmp_neq_f32_e32 vcc, -1.0, v20
	s_nop 1
	v_cndmask_b32_e32 v6, v142, v6, vcc
	v_cmp_lt_f32_e64 vcc, |v20|, s38
	s_nop 1
	v_cndmask_b32_e32 v52, v6, v20, vcc
; __device__ __forceinline__ void lru_phase(const Args& A, unsigned char* smem, const bool dry) {
;     ...
;             float ba[4], bx[4], sp[4];
; #pragma unroll
;             for (int dt = 0; dt < 4; ++dt) { const int ch = dir * 1024 + 64 * nb + 16 * dt + r16; ba[dt] = A.in[9][ch]; bx[dt] = A.in[11][ch];
;                 const float ml = -A.in[12][ch]; sp[dt] = ml > 20.f ? ml : log1pf(__expf(ml)); }
.LBB0_497:
	s_or_b64 exec, exec, s[8:9]
	s_waitcnt vmcnt(8)
	v_xor_b32_e32 v54, 0x80000000, v208
	v_cmp_ngt_f32_e32 vcc, s34, v208
	s_and_saveexec_b64 s[8:9], vcc
	s_cbranch_execz .LBB0_499
	v_mul_f32_e32 v6, 0xbfb8aa3b, v208
	v_exp_f32_e32 v20, v6
	s_nop 0
	v_add_f32_e32 v8, 1.0, v20
	v_frexp_mant_f32_e32 v10, v8
	v_cvt_f64_f32_e32 v[6:7], v8
	v_frexp_exp_i32_f64_e32 v6, v[6:7]
	v_cmp_gt_f32_e32 vcc, s35, v10
	v_add_f32_e32 v9, -1.0, v8
	v_sub_f32_e32 v11, v9, v8
	v_subbrev_co_u32_e32 v14, vcc, 0, v6, vcc
	v_sub_u32_e32 v6, 0, v14
	v_sub_f32_e32 v9, v20, v9
	v_add_f32_e32 v11, 1.0, v11
	v_ldexp_f32 v7, v8, v6
	v_add_f32_e32 v9, v9, v11
	v_add_f32_e32 v8, -1.0, v7
	v_add_f32_e32 v10, 1.0, v7
	v_ldexp_f32 v6, v9, v6
	v_add_f32_e32 v9, 1.0, v8
	v_add_f32_e32 v11, -1.0, v10
	v_sub_f32_e32 v9, v7, v9
	v_sub_f32_e32 v7, v7, v11
	v_add_f32_e32 v9, v6, v9
	v_add_f32_e32 v6, v6, v7
	v_add_f32_e32 v15, v10, v6
	v_rcp_f32_e32 v17, v15
	v_sub_f32_e32 v7, v15, v10
	v_sub_f32_e32 v16, v6, v7
	v_add_f32_e32 v7, v8, v9
	v_mul_f32_e32 v19, v7, v17
	v_sub_f32_e32 v6, v7, v8
	v_mul_f32_e32 v8, v15, v19
	v_fma_f32 v10, v19, v15, -v8
	v_fmac_f32_e32 v10, v19, v16
	v_sub_f32_e32 v18, v9, v6
	v_add_f32_e32 v6, v8, v10
	v_sub_f32_e32 v9, v7, v6
	v_pk_add_f32 v[12:13], v[6:7], v[8:9] neg_lo:[0,1] neg_hi:[0,1]
	v_mov_b32_e32 v11, v6
	v_pk_add_f32 v[6:7], v[12:13], v[10:11] neg_lo:[0,1] neg_hi:[0,1]
	v_cmp_neq_f32_e32 vcc, s37, v20
	v_add_f32_e32 v7, v18, v7
	v_add_f32_e32 v6, v6, v7
	v_add_f32_e32 v7, v9, v6
	v_mul_f32_e32 v18, v17, v7
	v_mul_f32_e32 v8, v15, v18
	v_fma_f32 v10, v18, v15, -v8
	v_fmac_f32_e32 v10, v18, v16
	v_sub_f32_e32 v9, v9, v7
	v_add_f32_e32 v15, v6, v9
	v_add_f32_e32 v6, v8, v10
	v_sub_f32_e32 v9, v7, v6
	v_pk_add_f32 v[12:13], v[6:7], v[8:9] neg_lo:[0,1] neg_hi:[0,1]
	v_mov_b32_e32 v11, v6
	v_pk_add_f32 v[6:7], v[12:13], v[10:11] neg_lo:[0,1] neg_hi:[0,1]
	s_nop 0
	v_add_f32_e32 v7, v15, v7
	v_add_f32_e32 v6, v6, v7
	v_add_f32_e32 v7, v19, v18
	v_add_f32_e32 v6, v9, v6
	v_sub_f32_e32 v8, v7, v19
	v_mul_f32_e32 v6, v17, v6
	v_sub_f32_e32 v8, v18, v8
	v_add_f32_e32 v8, v8, v6
	v_add_f32_e32 v10, v7, v8
	v_mul_f32_e32 v11, v10, v10
	v_fmamk_f32 v6, v11, 0x3e9b6dac, v132
	v_fmaak_f32 v49, v11, v6, 0x3f2aaada
	v_cvt_f32_i32_e32 v6, v14
	v_sub_f32_e32 v7, v10, v7
	v_sub_f32_e32 v7, v8, v7
	v_ldexp_f32 v12, v7, 1
	v_mul_f32_e32 v7, v10, v11
	v_ldexp_f32 v9, v10, 1
	v_pk_mul_f32 v[10:11], v[6:7], v[48:49]
	s_nop 0
	v_fma_f32 v8, v6, s36, -v10
	v_fmac_f32_e32 v8, 0xb102e308, v6
	v_pk_add_f32 v[6:7], v[10:11], v[8:9]
	s_nop 0
	v_sub_f32_e32 v9, v7, v9
	v_sub_f32_e32 v9, v11, v9
	v_add_f32_e32 v13, v12, v9
	v_mov_b32_e32 v12, v10
	v_pk_add_f32 v[10:11], v[6:7], v[10:11] neg_lo:[0,1] neg_hi:[0,1]
	v_pk_add_f32 v[14:15], v[6:7], v[12:13]
	v_mov_b32_e32 v9, v6
	v_mov_b32_e32 v11, v15
	v_pk_add_f32 v[16:17], v[8:9], v[10:11] neg_lo:[0,1] neg_hi:[0,1]
	v_pk_add_f32 v[8:9], v[8:9], v[10:11]
	v_mov_b32_e32 v12, v13
	v_pk_add_f32 v[10:11], v[8:9], v[6:7] op_sel:[1,0] op_sel_hi:[0,1] neg_lo:[0,1] neg_hi:[0,1]
	v_pk_add_f32 v[18:19], v[14:15], v[10:11] op_sel_hi:[1,0] neg_lo:[0,1] neg_hi:[0,1]
	v_mov_b32_e32 v14, v15
	v_mov_b32_e32 v15, v9
	v_pk_mov_b32 v[10:11], v[6:7], v[10:11] op_sel:[1,0]
	v_mov_b32_e32 v13, v6
	v_pk_add_f32 v[10:11], v[14:15], v[10:11] neg_lo:[0,1] neg_hi:[0,1]
	v_mov_b32_e32 v18, v16
	v_pk_add_f32 v[6:7], v[12:13], v[10:11] neg_lo:[0,1] neg_hi:[0,1]
	v_mov_b32_e32 v17, v9
	v_pk_add_f32 v[10:11], v[18:19], v[6:7]
	s_nop 0
	v_pk_add_f32 v[12:13], v[10:11], v[10:11] op_sel:[0,1] op_sel_hi:[1,0]
	s_nop 0
	v_pk_add_f32 v[8:9], v[8:9], v[12:13] op_sel:[1,0] op_sel_hi:[0,1]
	v_mov_b32_e32 v11, v8
	v_pk_add_f32 v[14:15], v[10:11], v[16:17] neg_lo:[0,1] neg_hi:[0,1]
	v_mov_b32_e32 v7, v12
	v_sub_f32_e32 v9, v10, v14
	v_pk_add_f32 v[6:7], v[6:7], v[14:15] neg_lo:[0,1] neg_hi:[0,1]
	v_sub_f32_e32 v9, v16, v9
	v_add_f32_e32 v6, v6, v9
	v_add_f32_e32 v6, v6, v7
	v_add_f32_e32 v6, v8, v6
	v_cndmask_b32_e32 v6, v140, v6, vcc
	v_cmp_ngt_f32_e32 vcc, -1.0, v20
	s_nop 1
	v_cndmask_b32_e32 v6, v141, v6, vcc
	v_cmp_neq_f32_e32 vcc, -1.0, v20
	s_nop 1
	v_cndmask_b32_e32 v6, v142, v6, vcc
	v_cmp_lt_f32_e64 vcc, |v20|, s38
	s_nop 1
	v_cndmask_b32_e32 v54, v6, v20, vcc
.LBB0_499:
	s_or_b64 exec, exec, s[8:9]
	s_waitcnt vmcnt(5)
	v_xor_b32_e32 v56, 0x80000000, v209
	v_cmp_ngt_f32_e32 vcc, s34, v209
	s_and_saveexec_b64 s[8:9], vcc
	s_cbranch_execz .LBB0_501
; __device__ __forceinline__ void lru_phase(const Args& A, unsigned char* smem, const bool dry) {
;     ...
;                 const float ml = -A.in[12][ch]; sp[dt] = ml > 20.f ? ml : log1pf(__expf(ml)); }
	v_mul_f32_e32 v6, 0xbfb8aa3b, v209
	v_exp_f32_e32 v20, v6
	s_nop 0
	v_add_f32_e32 v8, 1.0, v20
	v_frexp_mant_f32_e32 v10, v8
	v_cvt_f64_f32_e32 v[6:7], v8
	v_frexp_exp_i32_f64_e32 v6, v[6:7]
	v_cmp_gt_f32_e32 vcc, s35, v10
	v_add_f32_e32 v9, -1.0, v8
	v_sub_f32_e32 v11, v9, v8
	v_subbrev_co_u32_e32 v14, vcc, 0, v6, vcc
	v_sub_u32_e32 v6, 0, v14
	v_sub_f32_e32 v9, v20, v9
	v_add_f32_e32 v11, 1.0, v11
	v_ldexp_f32 v7, v8, v6
	v_add_f32_e32 v9, v9, v11
	v_add_f32_e32 v8, -1.0, v7
	v_add_f32_e32 v10, 1.0, v7
	v_ldexp_f32 v6, v9, v6
	v_add_f32_e32 v9, 1.0, v8
	v_add_f32_e32 v11, -1.0, v10
	v_sub_f32_e32 v9, v7, v9
	v_sub_f32_e32 v7, v7, v11
	v_add_f32_e32 v9, v6, v9
	v_add_f32_e32 v6, v6, v7
	v_add_f32_e32 v15, v10, v6
	v_rcp_f32_e32 v17, v15
	v_sub_f32_e32 v7, v15, v10
	v_sub_f32_e32 v16, v6, v7
	v_add_f32_e32 v7, v8, v9
	v_mul_f32_e32 v19, v7, v17
	v_sub_f32_e32 v6, v7, v8
	v_mul_f32_e32 v8, v15, v19
	v_fma_f32 v10, v19, v15, -v8
	v_fmac_f32_e32 v10, v19, v16
	v_sub_f32_e32 v18, v9, v6
	v_add_f32_e32 v6, v8, v10
	v_sub_f32_e32 v9, v7, v6
	v_pk_add_f32 v[12:13], v[6:7], v[8:9] neg_lo:[0,1] neg_hi:[0,1]
	v_mov_b32_e32 v11, v6
	v_pk_add_f32 v[6:7], v[12:13], v[10:11] neg_lo:[0,1] neg_hi:[0,1]
	v_cmp_neq_f32_e32 vcc, s37, v20
	v_add_f32_e32 v7, v18, v7
	v_add_f32_e32 v6, v6, v7
	v_add_f32_e32 v7, v9, v6
	v_mul_f32_e32 v18, v17, v7
	v_mul_f32_e32 v8, v15, v18
	v_fma_f32 v10, v18, v15, -v8
	v_fmac_f32_e32 v10, v18, v16
	v_sub_f32_e32 v9, v9, v7
	v_add_f32_e32 v15, v6, v9
	v_add_f32_e32 v6, v8, v10
	v_sub_f32_e32 v9, v7, v6
	v_pk_add_f32 v[12:13], v[6:7], v[8:9] neg_lo:[0,1] neg_hi:[0,1]
	v_mov_b32_e32 v11, v6
	v_pk_add_f32 v[6:7], v[12:13], v[10:11] neg_lo:[0,1] neg_hi:[0,1]
	s_nop 0
	v_add_f32_e32 v7, v15, v7
	v_add_f32_e32 v6, v6, v7
	v_add_f32_e32 v7, v19, v18
	v_add_f32_e32 v6, v9, v6
	v_sub_f32_e32 v8, v7, v19
	v_mul_f32_e32 v6, v17, v6
	v_sub_f32_e32 v8, v18, v8
	v_add_f32_e32 v8, v8, v6
	v_add_f32_e32 v10, v7, v8
	v_mul_f32_e32 v11, v10, v10
	v_fmamk_f32 v6, v11, 0x3e9b6dac, v132
	v_fmaak_f32 v49, v11, v6, 0x3f2aaada
	v_cvt_f32_i32_e32 v6, v14
	v_sub_f32_e32 v7, v10, v7
	v_sub_f32_e32 v7, v8, v7
	v_ldexp_f32 v12, v7, 1
	v_mul_f32_e32 v7, v10, v11
	v_ldexp_f32 v9, v10, 1
	v_pk_mul_f32 v[10:11], v[6:7], v[48:49]
	s_nop 0
	v_fma_f32 v8, v6, s36, -v10
	v_fmac_f32_e32 v8, 0xb102e308, v6
	v_pk_add_f32 v[6:7], v[10:11], v[8:9]
	s_nop 0
	v_sub_f32_e32 v9, v7, v9
	v_sub_f32_e32 v9, v11, v9
	v_add_f32_e32 v13, v12, v9
	v_mov_b32_e32 v12, v10
	v_pk_add_f32 v[10:11], v[6:7], v[10:11] neg_lo:[0,1] neg_hi:[0,1]
	v_pk_add_f32 v[14:15], v[6:7], v[12:13]
	v_mov_b32_e32 v9, v6
	v_mov_b32_e32 v11, v15
	v_pk_add_f32 v[16:17], v[8:9], v[10:11] neg_lo:[0,1] neg_hi:[0,1]
	v_pk_add_f32 v[8:9], v[8:9], v[10:11]
	v_mov_b32_e32 v12, v13
	v_pk_add_f32 v[10:11], v[8:9], v[6:7] op_sel:[1,0] op_sel_hi:[0,1] neg_lo:[0,1] neg_hi:[0,1]
	v_pk_add_f32 v[18:19], v[14:15], v[10:11] op_sel_hi:[1,0] neg_lo:[0,1] neg_hi:[0,1]
	v_mov_b32_e32 v14, v15
	v_mov_b32_e32 v15, v9
	v_pk_mov_b32 v[10:11], v[6:7], v[10:11] op_sel:[1,0]
	v_mov_b32_e32 v13, v6
	v_pk_add_f32 v[10:11], v[14:15], v[10:11] neg_lo:[0,1] neg_hi:[0,1]
	v_mov_b32_e32 v18, v16
	v_pk_add_f32 v[6:7], v[12:13], v[10:11] neg_lo:[0,1] neg_hi:[0,1]
	v_mov_b32_e32 v17, v9
	v_pk_add_f32 v[10:11], v[18:19], v[6:7]
	s_nop 0
	v_pk_add_f32 v[12:13], v[10:11], v[10:11] op_sel:[0,1] op_sel_hi:[1,0]
	s_nop 0
	v_pk_add_f32 v[8:9], v[8:9], v[12:13] op_sel:[1,0] op_sel_hi:[0,1]
	v_mov_b32_e32 v11, v8
	v_pk_add_f32 v[14:15], v[10:11], v[16:17] neg_lo:[0,1] neg_hi:[0,1]
	v_mov_b32_e32 v7, v12
	v_sub_f32_e32 v9, v10, v14
	v_pk_add_f32 v[6:7], v[6:7], v[14:15] neg_lo:[0,1] neg_hi:[0,1]
	v_sub_f32_e32 v9, v16, v9
	v_add_f32_e32 v6, v6, v9
	v_add_f32_e32 v6, v6, v7
	v_add_f32_e32 v6, v8, v6
	v_cndmask_b32_e32 v6, v140, v6, vcc
	v_cmp_ngt_f32_e32 vcc, -1.0, v20
	s_nop 1
	v_cndmask_b32_e32 v6, v141, v6, vcc
	v_cmp_neq_f32_e32 vcc, -1.0, v20
	s_nop 1
	v_cndmask_b32_e32 v6, v142, v6, vcc
	v_cmp_lt_f32_e64 vcc, |v20|, s38
	s_nop 1
	v_cndmask_b32_e32 v56, v6, v20, vcc
; __device__ __forceinline__ void lru_phase(const Args& A, unsigned char* smem, const bool dry) {
;     ...
;                 const float ml = -A.in[12][ch]; sp[dt] = ml > 20.f ? ml : log1pf(__expf(ml)); }
.LBB0_501:
	s_or_b64 exec, exec, s[8:9]
	s_nop 0
	s_waitcnt vmcnt(2)
	v_xor_b32_e32 v58, 0x80000000, v210
	v_cmp_ngt_f32_e32 vcc, s34, v210
	s_and_saveexec_b64 s[8:9], vcc
	s_cbranch_execz .LBB0_503
	v_mul_f32_e32 v0, 0xbfb8aa3b, v210
	v_exp_f32_e32 v14, v0
	s_nop 0
	v_add_f32_e32 v2, 1.0, v14
	v_frexp_mant_f32_e32 v4, v2
	v_cvt_f64_f32_e32 v[0:1], v2
	v_frexp_exp_i32_f64_e32 v0, v[0:1]
	v_cmp_gt_f32_e32 vcc, s35, v4
	v_add_f32_e32 v3, -1.0, v2
	v_sub_f32_e32 v5, v3, v2
	v_subbrev_co_u32_e32 v8, vcc, 0, v0, vcc
	v_sub_u32_e32 v0, 0, v8
	v_sub_f32_e32 v3, v14, v3
	v_add_f32_e32 v5, 1.0, v5
	v_ldexp_f32 v1, v2, v0
	v_add_f32_e32 v3, v3, v5
	v_add_f32_e32 v2, -1.0, v1
	v_add_f32_e32 v4, 1.0, v1
	v_ldexp_f32 v0, v3, v0
	v_add_f32_e32 v3, 1.0, v2
	v_add_f32_e32 v5, -1.0, v4
	v_sub_f32_e32 v3, v1, v3
	v_sub_f32_e32 v1, v1, v5
	v_add_f32_e32 v3, v0, v3
	v_add_f32_e32 v0, v0, v1
	v_add_f32_e32 v9, v4, v0
	v_rcp_f32_e32 v11, v9
	v_sub_f32_e32 v1, v9, v4
	v_sub_f32_e32 v10, v0, v1
	v_add_f32_e32 v1, v2, v3
	v_mul_f32_e32 v13, v1, v11
	v_sub_f32_e32 v0, v1, v2
	v_mul_f32_e32 v2, v9, v13
	v_fma_f32 v4, v13, v9, -v2
	v_fmac_f32_e32 v4, v13, v10
	v_sub_f32_e32 v12, v3, v0
	v_add_f32_e32 v0, v2, v4
	v_sub_f32_e32 v3, v1, v0
	v_pk_add_f32 v[6:7], v[0:1], v[2:3] neg_lo:[0,1] neg_hi:[0,1]
	v_mov_b32_e32 v5, v0
	v_pk_add_f32 v[0:1], v[6:7], v[4:5] neg_lo:[0,1] neg_hi:[0,1]
	v_cmp_neq_f32_e32 vcc, s37, v14
	v_add_f32_e32 v1, v12, v1
	v_add_f32_e32 v0, v0, v1
	v_add_f32_e32 v1, v3, v0
	v_mul_f32_e32 v12, v11, v1
	v_mul_f32_e32 v2, v9, v12
	v_fma_f32 v4, v12, v9, -v2
	v_fmac_f32_e32 v4, v12, v10
	v_sub_f32_e32 v3, v3, v1
	v_add_f32_e32 v9, v0, v3
	v_add_f32_e32 v0, v2, v4
	v_sub_f32_e32 v3, v1, v0
	v_pk_add_f32 v[6:7], v[0:1], v[2:3] neg_lo:[0,1] neg_hi:[0,1]
	v_mov_b32_e32 v5, v0
	v_pk_add_f32 v[0:1], v[6:7], v[4:5] neg_lo:[0,1] neg_hi:[0,1]
	s_nop 0
	v_add_f32_e32 v1, v9, v1
	v_add_f32_e32 v0, v0, v1
	v_add_f32_e32 v1, v13, v12
	v_add_f32_e32 v0, v3, v0
	v_sub_f32_e32 v2, v1, v13
	v_mul_f32_e32 v0, v11, v0
	v_sub_f32_e32 v2, v12, v2
	v_add_f32_e32 v2, v2, v0
	v_add_f32_e32 v4, v1, v2
	v_mul_f32_e32 v5, v4, v4
	v_fmamk_f32 v0, v5, 0x3e9b6dac, v132
	v_fmaak_f32 v49, v5, v0, 0x3f2aaada
	v_cvt_f32_i32_e32 v0, v8
	v_sub_f32_e32 v1, v4, v1
	v_sub_f32_e32 v1, v2, v1
	v_ldexp_f32 v6, v1, 1
	v_mul_f32_e32 v1, v4, v5
	v_ldexp_f32 v3, v4, 1
	v_pk_mul_f32 v[4:5], v[0:1], v[48:49]
	s_nop 0
	v_fma_f32 v2, v0, s36, -v4
	v_fmac_f32_e32 v2, 0xb102e308, v0
	v_pk_add_f32 v[0:1], v[4:5], v[2:3]
	s_nop 0
	v_sub_f32_e32 v3, v1, v3
	v_sub_f32_e32 v3, v5, v3
	v_add_f32_e32 v7, v6, v3
	v_mov_b32_e32 v6, v4
	v_pk_add_f32 v[4:5], v[0:1], v[4:5] neg_lo:[0,1] neg_hi:[0,1]
	v_pk_add_f32 v[8:9], v[0:1], v[6:7]
	v_mov_b32_e32 v3, v0
	v_mov_b32_e32 v5, v9
	v_pk_add_f32 v[10:11], v[2:3], v[4:5] neg_lo:[0,1] neg_hi:[0,1]
	v_pk_add_f32 v[2:3], v[2:3], v[4:5]
	v_mov_b32_e32 v6, v7
	v_pk_add_f32 v[4:5], v[2:3], v[0:1] op_sel:[1,0] op_sel_hi:[0,1] neg_lo:[0,1] neg_hi:[0,1]
	v_pk_add_f32 v[12:13], v[8:9], v[4:5] op_sel_hi:[1,0] neg_lo:[0,1] neg_hi:[0,1]
	v_mov_b32_e32 v8, v9
	v_mov_b32_e32 v9, v3
	v_pk_mov_b32 v[4:5], v[0:1], v[4:5] op_sel:[1,0]
	v_mov_b32_e32 v7, v0
	v_pk_add_f32 v[4:5], v[8:9], v[4:5] neg_lo:[0,1] neg_hi:[0,1]
	v_mov_b32_e32 v12, v10
	v_pk_add_f32 v[0:1], v[6:7], v[4:5] neg_lo:[0,1] neg_hi:[0,1]
	v_mov_b32_e32 v11, v3
	v_pk_add_f32 v[4:5], v[12:13], v[0:1]
	s_nop 0
	v_pk_add_f32 v[6:7], v[4:5], v[4:5] op_sel:[0,1] op_sel_hi:[1,0]
	s_nop 0
	v_pk_add_f32 v[2:3], v[2:3], v[6:7] op_sel:[1,0] op_sel_hi:[0,1]
	v_mov_b32_e32 v5, v2
	v_pk_add_f32 v[8:9], v[4:5], v[10:11] neg_lo:[0,1] neg_hi:[0,1]
	v_mov_b32_e32 v1, v6
	v_sub_f32_e32 v3, v4, v8
	v_pk_add_f32 v[0:1], v[0:1], v[8:9] neg_lo:[0,1] neg_hi:[0,1]
	v_sub_f32_e32 v3, v10, v3
	v_add_f32_e32 v0, v0, v3
	v_add_f32_e32 v0, v0, v1
	v_add_f32_e32 v0, v2, v0
	v_cndmask_b32_e32 v0, v140, v0, vcc
	v_cmp_ngt_f32_e32 vcc, -1.0, v14
	s_nop 1
	v_cndmask_b32_e32 v0, v141, v0, vcc
	v_cmp_neq_f32_e32 vcc, -1.0, v14
	s_nop 1
	v_cndmask_b32_e32 v0, v142, v0, vcc
	v_cmp_lt_f32_e64 vcc, |v14|, s38
	s_nop 1
	v_cndmask_b32_e32 v58, v0, v14, vcc
